# decode-row retention item: q/k, gate, V and 16 state-row loads issued together with counted waits; no store drain before the gate (on top of shorter barrier chain)
# speedup vs baseline: 1.0107x; 1.0033x over previous
.LBB0_530:
	s_or_saveexec_b64 s[4:5], s[4:5]
	v_ashrrev_i32_e32 v55, 31, v54
	s_xor_b64 exec, exec, s[4:5]
	s_lshl_b64 s[0:1], s[0:1], 1
	s_add_u32 s0, s67, s0
	s_addc_u32 s1, s68, s1
	s_lshl_b32 s8, s11, 1
	s_add_u32 s0, s0, s8
	s_addc_u32 s1, s1, 0
	v_lshl_add_u64 v[0:1], v[54:55], 1, s[0:1]
	s_or_b64 s[6:7], s[6:7], exec
	s_or_b64 exec, exec, s[4:5]
	v_lshl_add_u32 v72, v54, 2, 0
	v_readlane_b32 s50, v252, 20
	v_readlane_b32 s51, v252, 21
	s_lshl_b64 s[12:13], s[38:39], 11
	s_lshl_b32 s4, s2, 9
	s_add_u32 s12, s69, s12
	s_addc_u32 s13, s70, s13
	s_add_u32 s12, s12, s4
	s_addc_u32 s13, s13, 0
	v_lshlrev_b32_e32 v115, 1, v54
	s_and_saveexec_b64 s[0:1], s[6:7]
	s_cbranch_execz .Lrs_qk_issued
	global_load_ushort v98, v[0:1], off
	global_load_ushort v114, v115, s[12:13]
.Lrs_qk_issued:
	s_or_b64 exec, exec, s[0:1]
	s_lshl_b64 s[0:1], s[38:39], 11
	s_add_u32 s0, s3, s0
	s_addc_u32 s1, s66, s1
	s_lshl_b32 s4, s2, 9
	s_add_u32 s0, s0, s4
	s_addc_u32 s1, s1, 0
	v_lshlrev_b32_e32 v100, 2, v54
	v_and_b32_e32 v100, 0xfc, v100
	v_lshlrev_b32_e32 v101, 1, v100
	v_ashrrev_i32_e32 v73, 6, v54
	global_load_dwordx2 v[102:103], v101, s[0:1]
	v_lshlrev_b32_e32 v52, 2, v100
	s_lshl_b32 s0, s10, 7
	s_mov_b32 s1, s39
	v_lshlrev_b32_e32 v104, 4, v73
	v_ashrrev_i32_e32 v105, 31, v104
	v_lshl_add_u64 v[104:105], v[104:105], 0, s[0:1]
	v_lshlrev_b64 v[104:105], 10, v[104:105]
	v_lshl_add_u64 v[106:107], s[50:51], 0, v[104:105]
	v_lshl_add_u64 v[106:107], v[106:107], 0, v[52:53]
	global_load_dwordx4 v[48:51], v[106:107], off nt
	global_load_dwordx4 v[64:67], v[106:107], off offset:1024 nt
	global_load_dwordx4 v[68:71], v[106:107], off offset:2048 nt
	global_load_dwordx4 v[82:85], v[106:107], off offset:3072 nt
	v_lshl_add_u64 v[62:63], s[30:31], 0, v[104:105]
	v_add_co_u32_e32 v108, vcc, s62, v106
	v_lshl_add_u64 v[62:63], v[62:63], 0, v[52:53]
	s_nop 0
	v_addc_co_u32_e32 v109, vcc, 0, v107, vcc
	v_add_co_u32_e32 v110, vcc, s63, v106
	s_nop 1
	v_addc_co_u32_e32 v111, vcc, 0, v107, vcc
	global_load_dwordx4 v[44:47], v[110:111], off offset:-4096 nt
	global_load_dwordx4 v[40:43], v[108:109], off offset:1024 nt
	global_load_dwordx4 v[36:39], v[108:109], off offset:2048 nt
	global_load_dwordx4 v[32:35], v[108:109], off offset:3072 nt
	global_load_dwordx4 v[28:31], v[110:111], off nt
	global_load_dwordx4 v[24:27], v[110:111], off offset:1024 nt
	global_load_dwordx4 v[20:23], v[110:111], off offset:2048 nt
	global_load_dwordx4 v[16:19], v[110:111], off offset:3072 nt
	v_add_co_u32_e32 v108, vcc, s64, v106
	s_nop 1
	v_addc_co_u32_e32 v109, vcc, 0, v107, vcc
	global_load_dwordx4 v[12:15], v[108:109], off nt
	global_load_dwordx4 v[8:11], v[108:109], off offset:1024 nt
	global_load_dwordx4 v[4:7], v[108:109], off offset:2048 nt
	global_load_dwordx4 v[0:3], v[108:109], off offset:3072 nt
	s_and_saveexec_b64 s[8:9], s[6:7]
	s_cbranch_execz .Lrs_qk_done
	s_waitcnt vmcnt(17)
	v_lshlrev_b32_e32 v98, 16, v98
	ds_write_b32 v72, v98
.Lrs_qk_done:
	s_or_b64 exec, exec, s[8:9]
	v_cvt_f32_ubyte0_e32 v112, s2
	v_sub_f32_e32 v112, 0xc0a00000, v112
	s_mov_b32 s4, 0xc2fc0000
	v_cmp_gt_f32_e32 vcc, s4, v112
	s_and_b64 s[4:5], vcc, exec
	s_nop 0
	v_cndmask_b32_e32 v113, 0, v79, vcc
	v_add_f32_e32 v112, v112, v113
	v_exp_f32_e32 v112, v112
	s_cselect_b32 s4, 0xffffffc0, 0
	s_waitcnt lgkmcnt(0)
	s_barrier
	v_ldexp_f32 v60, v112, s4
	v_and_b32_e32 v80, 0xffffffc0, v54
	v_add_u32_e32 v80, 0, v80
	v_mov_b32_e32 v61, 0
	v_sub_f32_e32 v60, 1.0, v60
	v_readlane_b32 s44, v252, 14
	v_readlane_b32 s50, v252, 20
	v_readlane_b32 s51, v252, 21
	v_readlane_b32 s45, v252, 15
	v_readlane_b32 s46, v252, 16
	v_readlane_b32 s47, v252, 17
	v_readlane_b32 s48, v252, 18
	v_readlane_b32 s49, v252, 19
	v_readlane_b32 s52, v252, 22
	v_readlane_b32 s53, v252, 23
	v_readlane_b32 s54, v252, 24
	v_readlane_b32 s55, v252, 25
	v_readlane_b32 s56, v252, 26
	v_readlane_b32 s57, v252, 27
	v_readlane_b32 s58, v252, 28
	v_readlane_b32 s59, v252, 29
	s_movk_i32 s0, 0x3c0
	s_waitcnt vmcnt(16)
	v_lshlrev_b32_e32 v56, 16, v102
	v_and_b32_e32 v57, 0xffff0000, v102
	v_lshlrev_b32_e32 v58, 16, v103
	v_and_b32_e32 v59, 0xffff0000, v103
	ds_read_b128 v[86:89], v80 offset:512
	ds_read_b128 v[90:93], v80
	s_waitcnt lgkmcnt(1)
	v_pk_mul_f32 v[94:95], v[86:87], v[56:57] op_sel_hi:[0,1]
	v_pk_mul_f32 v[96:97], v[86:87], v[58:59] op_sel_hi:[0,1]
	s_waitcnt vmcnt(15)
	v_pk_fma_f32 v[50:51], v[60:61], v[50:51], v[96:97] op_sel_hi:[0,1,1]
	v_pk_fma_f32 v[48:49], v[60:61], v[48:49], v[94:95] op_sel_hi:[0,1,1]
	global_store_dwordx4 v[62:63], v[48:51], off nt
	s_waitcnt lgkmcnt(0)
	v_pk_fma_f32 v[94:95], v[90:91], v[50:51], 0 op_sel_hi:[0,1,0]
	v_pk_fma_f32 v[96:97], v[90:91], v[48:49], 0 op_sel_hi:[0,1,0]
	v_pk_mul_f32 v[48:49], v[86:87], v[56:57] op_sel:[1,0]
	v_pk_mul_f32 v[50:51], v[86:87], v[58:59] op_sel:[1,0]
	s_waitcnt vmcnt(15)
	v_pk_fma_f32 v[48:49], v[60:61], v[64:65], v[48:49] op_sel_hi:[0,1,1]
	v_pk_fma_f32 v[50:51], v[60:61], v[66:67], v[50:51] op_sel_hi:[0,1,1]
	global_store_dwordx4 v[62:63], v[48:51], off offset:1024 nt
	v_pk_fma_f32 v[64:65], v[90:91], v[50:51], v[94:95] op_sel:[1,0,0]
	v_pk_fma_f32 v[66:67], v[90:91], v[48:49], v[96:97] op_sel:[1,0,0]
	v_pk_mul_f32 v[48:49], v[88:89], v[56:57] op_sel_hi:[0,1]
	v_pk_mul_f32 v[50:51], v[88:89], v[58:59] op_sel_hi:[0,1]
	s_waitcnt vmcnt(15)
	v_pk_fma_f32 v[50:51], v[60:61], v[70:71], v[50:51] op_sel_hi:[0,1,1]
	v_pk_fma_f32 v[48:49], v[60:61], v[68:69], v[48:49] op_sel_hi:[0,1,1]
	global_store_dwordx4 v[62:63], v[48:51], off offset:2048 nt
	v_pk_fma_f32 v[66:67], v[92:93], v[48:49], v[66:67] op_sel_hi:[0,1,1]
	v_pk_fma_f32 v[64:65], v[92:93], v[50:51], v[64:65] op_sel_hi:[0,1,1]
	v_mov_b32_e32 v48, v89
	v_pk_mul_f32 v[68:69], v[48:49], v[56:57] op_sel_hi:[0,1]
	v_pk_mul_f32 v[48:49], v[48:49], v[58:59] op_sel_hi:[0,1]
	s_waitcnt vmcnt(15)
	v_pk_fma_f32 v[50:51], v[60:61], v[84:85], v[48:49] op_sel_hi:[0,1,1]
	v_pk_fma_f32 v[48:49], v[60:61], v[82:83], v[68:69] op_sel_hi:[0,1,1]
	v_mov_b32_e32 v68, v93
	global_store_dwordx4 v[62:63], v[48:51], off offset:3072 nt
	v_pk_fma_f32 v[64:65], v[68:69], v[50:51], v[64:65] op_sel_hi:[0,1,1]
	v_pk_fma_f32 v[66:67], v[68:69], v[48:49], v[66:67] op_sel_hi:[0,1,1]
	ds_read_b128 v[48:51], v80 offset:528
	s_waitcnt lgkmcnt(0)
	v_pk_mul_f32 v[70:71], v[48:49], v[58:59] op_sel_hi:[0,1]
	s_waitcnt vmcnt(15)
	v_pk_fma_f32 v[84:85], v[60:61], v[46:47], v[70:71] op_sel_hi:[0,1,1]
	v_add_co_u32_e32 v70, vcc, s62, v62
	v_pk_mul_f32 v[68:69], v[48:49], v[56:57] op_sel_hi:[0,1]
	s_nop 0
	v_addc_co_u32_e32 v71, vcc, 0, v63, vcc
	v_pk_fma_f32 v[82:83], v[60:61], v[44:45], v[68:69] op_sel_hi:[0,1,1]
	v_add_co_u32_e32 v68, vcc, s63, v62
	s_nop 1
	v_addc_co_u32_e32 v69, vcc, 0, v63, vcc
	global_store_dwordx4 v[68:69], v[82:85], off offset:-4096 nt
	ds_read_b128 v[86:89], v80 offset:16
	ds_read_b128 v[90:93], v80 offset:32
	ds_read_b128 v[44:47], v80 offset:48
	s_waitcnt lgkmcnt(2)
	v_pk_fma_f32 v[66:67], v[86:87], v[82:83], v[66:67] op_sel_hi:[0,1,1]
	v_pk_mul_f32 v[82:83], v[48:49], v[56:57] op_sel:[1,0]
	v_pk_mul_f32 v[48:49], v[48:49], v[58:59] op_sel:[1,0]
	v_pk_fma_f32 v[64:65], v[86:87], v[84:85], v[64:65] op_sel_hi:[0,1,1]
	s_waitcnt vmcnt(15)
	v_pk_fma_f32 v[42:43], v[60:61], v[42:43], v[48:49] op_sel_hi:[0,1,1]
	v_pk_fma_f32 v[40:41], v[60:61], v[40:41], v[82:83] op_sel_hi:[0,1,1]
	global_store_dwordx4 v[70:71], v[40:43], off offset:1024 nt
	v_pk_mul_f32 v[48:49], v[50:51], v[56:57] op_sel_hi:[0,1]
	s_waitcnt vmcnt(15)
	v_pk_fma_f32 v[36:37], v[60:61], v[36:37], v[48:49] op_sel_hi:[0,1,1]
	v_pk_fma_f32 v[42:43], v[86:87], v[42:43], v[64:65] op_sel:[1,0,0]
	v_pk_mul_f32 v[64:65], v[50:51], v[58:59] op_sel_hi:[0,1]
	v_pk_fma_f32 v[40:41], v[86:87], v[40:41], v[66:67] op_sel:[1,0,0]
	v_pk_fma_f32 v[38:39], v[60:61], v[38:39], v[64:65] op_sel_hi:[0,1,1]
	global_store_dwordx4 v[70:71], v[36:39], off offset:2048 nt
	s_nop 1
	v_pk_fma_f32 v[36:37], v[88:89], v[36:37], v[40:41] op_sel_hi:[0,1,1]
	v_mov_b32_e32 v40, v51
	v_pk_fma_f32 v[38:39], v[88:89], v[38:39], v[42:43] op_sel_hi:[0,1,1]
	v_pk_mul_f32 v[42:43], v[40:41], v[56:57] op_sel_hi:[0,1]
	v_pk_mul_f32 v[40:41], v[40:41], v[58:59] op_sel_hi:[0,1]
	s_waitcnt vmcnt(15)
	v_pk_fma_f32 v[34:35], v[60:61], v[34:35], v[40:41] op_sel_hi:[0,1,1]
	v_pk_fma_f32 v[32:33], v[60:61], v[32:33], v[42:43] op_sel_hi:[0,1,1]
	v_mov_b32_e32 v40, v89
	global_store_dwordx4 v[70:71], v[32:35], off offset:3072 nt
	v_pk_fma_f32 v[38:39], v[40:41], v[34:35], v[38:39] op_sel_hi:[0,1,1]
	v_pk_fma_f32 v[36:37], v[40:41], v[32:33], v[36:37] op_sel_hi:[0,1,1]
	ds_read_b128 v[32:35], v80 offset:544
	s_waitcnt lgkmcnt(0)
	v_pk_mul_f32 v[40:41], v[32:33], v[56:57] op_sel_hi:[0,1]
	v_pk_mul_f32 v[42:43], v[32:33], v[58:59] op_sel_hi:[0,1]
	s_waitcnt vmcnt(15)
	v_pk_fma_f32 v[30:31], v[60:61], v[30:31], v[42:43] op_sel_hi:[0,1,1]
	v_pk_fma_f32 v[28:29], v[60:61], v[28:29], v[40:41] op_sel_hi:[0,1,1]
	global_store_dwordx4 v[68:69], v[28:31], off nt
	s_nop 1
	v_pk_fma_f32 v[28:29], v[90:91], v[28:29], v[36:37] op_sel_hi:[0,1,1]
	v_pk_mul_f32 v[36:37], v[32:33], v[56:57] op_sel:[1,0]
	v_pk_mul_f32 v[32:33], v[32:33], v[58:59] op_sel:[1,0]
	v_pk_fma_f32 v[30:31], v[90:91], v[30:31], v[38:39] op_sel_hi:[0,1,1]
	s_waitcnt vmcnt(15)
	v_pk_fma_f32 v[26:27], v[60:61], v[26:27], v[32:33] op_sel_hi:[0,1,1]
	v_pk_fma_f32 v[24:25], v[60:61], v[24:25], v[36:37] op_sel_hi:[0,1,1]
	global_store_dwordx4 v[68:69], v[24:27], off offset:1024 nt
	s_nop 1
	v_pk_fma_f32 v[26:27], v[90:91], v[26:27], v[30:31] op_sel:[1,0,0]
	v_pk_fma_f32 v[24:25], v[90:91], v[24:25], v[28:29] op_sel:[1,0,0]
	v_pk_mul_f32 v[28:29], v[34:35], v[56:57] op_sel_hi:[0,1]
	v_pk_mul_f32 v[30:31], v[34:35], v[58:59] op_sel_hi:[0,1]
	s_waitcnt vmcnt(15)
	v_pk_fma_f32 v[22:23], v[60:61], v[22:23], v[30:31] op_sel_hi:[0,1,1]
	v_pk_fma_f32 v[20:21], v[60:61], v[20:21], v[28:29] op_sel_hi:[0,1,1]
	global_store_dwordx4 v[68:69], v[20:23], off offset:2048 nt
	s_nop 1
	v_pk_fma_f32 v[20:21], v[92:93], v[20:21], v[24:25] op_sel_hi:[0,1,1]
	v_mov_b32_e32 v24, v35
	v_pk_fma_f32 v[22:23], v[92:93], v[22:23], v[26:27] op_sel_hi:[0,1,1]
	v_pk_mul_f32 v[26:27], v[24:25], v[56:57] op_sel_hi:[0,1]
	v_pk_mul_f32 v[24:25], v[24:25], v[58:59] op_sel_hi:[0,1]
	s_waitcnt vmcnt(15)
	v_pk_fma_f32 v[18:19], v[60:61], v[18:19], v[24:25] op_sel_hi:[0,1,1]
	v_pk_fma_f32 v[16:17], v[60:61], v[16:17], v[26:27] op_sel_hi:[0,1,1]
	v_mov_b32_e32 v24, v93
	global_store_dwordx4 v[68:69], v[16:19], off offset:3072 nt
	v_pk_fma_f32 v[22:23], v[24:25], v[18:19], v[22:23] op_sel_hi:[0,1,1]
	v_pk_fma_f32 v[20:21], v[24:25], v[16:17], v[20:21] op_sel_hi:[0,1,1]
	ds_read_b128 v[16:19], v80 offset:560
	s_waitcnt lgkmcnt(0)
	v_pk_mul_f32 v[24:25], v[16:17], v[56:57] op_sel_hi:[0,1]
	v_pk_mul_f32 v[26:27], v[16:17], v[58:59] op_sel_hi:[0,1]
	s_waitcnt vmcnt(15)
	v_pk_fma_f32 v[12:13], v[60:61], v[12:13], v[24:25] op_sel_hi:[0,1,1]
	v_add_co_u32_e32 v24, vcc, s64, v62
	v_pk_fma_f32 v[14:15], v[60:61], v[14:15], v[26:27] op_sel_hi:[0,1,1]
	s_nop 0
	v_addc_co_u32_e32 v25, vcc, 0, v63, vcc
	global_store_dwordx4 v[24:25], v[12:15], off nt
	v_cmp_gt_i32_e32 vcc, s61, v54
	s_nop 0
	v_pk_fma_f32 v[12:13], v[44:45], v[12:13], v[20:21] op_sel_hi:[0,1,1]
	v_pk_mul_f32 v[20:21], v[16:17], v[56:57] op_sel:[1,0]
	v_pk_mul_f32 v[16:17], v[16:17], v[58:59] op_sel:[1,0]
	v_pk_fma_f32 v[14:15], v[44:45], v[14:15], v[22:23] op_sel_hi:[0,1,1]
	s_waitcnt vmcnt(15)
	v_pk_fma_f32 v[10:11], v[60:61], v[10:11], v[16:17] op_sel_hi:[0,1,1]
	v_pk_fma_f32 v[8:9], v[60:61], v[8:9], v[20:21] op_sel_hi:[0,1,1]
	global_store_dwordx4 v[24:25], v[8:11], off offset:1024 nt
	s_nop 1
	v_pk_fma_f32 v[10:11], v[44:45], v[10:11], v[14:15] op_sel:[1,0,0]
	v_pk_fma_f32 v[8:9], v[44:45], v[8:9], v[12:13] op_sel:[1,0,0]
	v_pk_mul_f32 v[12:13], v[18:19], v[56:57] op_sel_hi:[0,1]
	v_pk_mul_f32 v[14:15], v[18:19], v[58:59] op_sel_hi:[0,1]
	s_waitcnt vmcnt(15)
	v_pk_fma_f32 v[6:7], v[60:61], v[6:7], v[14:15] op_sel_hi:[0,1,1]
	v_pk_fma_f32 v[4:5], v[60:61], v[4:5], v[12:13] op_sel_hi:[0,1,1]
	global_store_dwordx4 v[24:25], v[4:7], off offset:2048 nt
	s_nop 1
	v_pk_fma_f32 v[4:5], v[46:47], v[4:5], v[8:9] op_sel_hi:[0,1,1]
	v_mov_b32_e32 v8, v19
	v_pk_fma_f32 v[6:7], v[46:47], v[6:7], v[10:11] op_sel_hi:[0,1,1]
	v_pk_mul_f32 v[10:11], v[8:9], v[56:57] op_sel_hi:[0,1]
	v_pk_mul_f32 v[8:9], v[8:9], v[58:59] op_sel_hi:[0,1]
	s_waitcnt vmcnt(15)
	v_pk_fma_f32 v[2:3], v[60:61], v[2:3], v[8:9] op_sel_hi:[0,1,1]
	v_pk_fma_f32 v[0:1], v[60:61], v[0:1], v[10:11] op_sel_hi:[0,1,1]
	v_mov_b32_e32 v8, v47
	global_store_dwordx4 v[24:25], v[0:3], off offset:3072 nt
	s_nop 1
	v_pk_fma_f32 v[0:1], v[8:9], v[0:1], v[4:5] op_sel_hi:[0,1,1]
	v_mul_lo_u32 v4, v73, s0
	v_pk_fma_f32 v[2:3], v[8:9], v[2:3], v[6:7] op_sel_hi:[0,1,1]
	v_add3_u32 v4, v80, v4, v52
	ds_write_b128 v4, v[0:3] offset:1088
	s_waitcnt lgkmcnt(0)
	s_barrier
	s_and_saveexec_b64 s[0:1], vcc
	s_cbranch_execz .LBB0_536
	v_add_u32_e32 v6, 64, v72
	ds_read2st64_b32 v[0:1], v6 offset0:4 offset1:8
	ds_read2st64_b32 v[2:3], v6 offset0:12 offset1:16
	ds_read2st64_b32 v[4:5], v6 offset0:20 offset1:24
	s_waitcnt lgkmcnt(2)
	v_add_f32_e32 v0, 0, v0
	v_add_f32_e32 v7, v0, v1
	ds_read2st64_b32 v[0:1], v6 offset0:28 offset1:32
	s_waitcnt lgkmcnt(2)
	v_add_f32_e32 v2, v7, v2
	v_add_f32_e32 v2, v2, v3
	s_waitcnt lgkmcnt(1)
	v_add_f32_e32 v2, v2, v4
	v_add_f32_e32 v2, v2, v5
	s_waitcnt lgkmcnt(0)
	v_add_f32_e32 v0, v2, v0
	v_add_f32_e32 v61, v0, v1

.LBB0_538:
	s_or_b64 exec, exec, s[4:5]
	s_waitcnt lgkmcnt(0)
	s_barrier
	s_and_saveexec_b64 s[4:5], vcc
	s_cbranch_execz .LBB0_540
	s_lshl_b64 s[0:1], s[38:39], 10
	v_readlane_b32 s8, v252, 0
	s_lshl_b32 s2, s2, 8
	s_lshl_b64 s[0:1], s[0:1], 1
	v_readlane_b32 s12, v252, 4
	v_readlane_b32 s13, v252, 5
	s_add_u32 s6, s12, s0
	s_addc_u32 s7, s13, s1
	s_lshl_b32 s2, s2, 1
	s_add_u32 s6, s6, s2
	s_addc_u32 s7, s7, 0
	s_add_u32 s0, s69, s0
	s_addc_u32 s1, s70, s1
	s_add_u32 s0, s0, s2
	s_addc_u32 s1, s1, 0
	v_lshlrev_b64 v[8:9], 1, v[54:55]
	v_lshl_add_u64 v[0:1], s[0:1], 0, v[8:9]
	ds_read_b128 v[0:3], v53 offset:1024
	ds_read_b128 v[4:7], v53 offset:1040
	v_readlane_b32 s9, v252, 1
	v_readlane_b32 s10, v252, 2
	v_readlane_b32 s11, v252, 3
	s_waitcnt lgkmcnt(1)
	v_add_f32_e32 v0, 0, v0
	v_add_f32_e32 v0, v0, v1
	v_add_f32_e32 v0, v0, v2
	v_add_f32_e32 v0, v0, v3
	s_waitcnt lgkmcnt(0)
	v_add_f32_e32 v0, v0, v4
	v_add_f32_e32 v0, v0, v5
	v_add_f32_e32 v0, v0, v6
	v_add_f32_e32 v0, v0, v7
	v_fmamk_f32 v0, v0, 0x3b800000, v75
	v_mul_f32_e32 v1, 0x4f800000, v0
	v_cmp_gt_f32_e32 vcc, s65, v0
	v_readlane_b32 s14, v252, 6
	v_readlane_b32 s15, v252, 7
	v_cndmask_b32_e32 v0, v0, v1, vcc
	v_sqrt_f32_e32 v1, v0
	s_nop 0
	v_add_u32_e32 v2, -1, v1
	v_add_u32_e32 v3, 1, v1
	v_fma_f32 v4, -v2, v1, v0
	v_fma_f32 v5, -v3, v1, v0
	v_cmp_ge_f32_e64 s[0:1], 0, v4
	s_nop 1
	v_cndmask_b32_e64 v1, v1, v2, s[0:1]
	v_cmp_lt_f32_e64 s[0:1], 0, v5
	v_lshlrev_b32_e32 v5, 16, v114
	v_cndmask_b32_e64 v1, v1, v3, s[0:1]
	v_mul_f32_e32 v2, 0x37800000, v1
	v_cndmask_b32_e32 v1, v1, v2, vcc
	v_cmp_class_f32_e32 vcc, v0, v76
	v_mul_f32_e32 v6, 0xbfb8aa3b, v5
	v_exp_f32_e32 v6, v6
	v_cndmask_b32_e32 v0, v1, v0, vcc
	v_div_scale_f32 v1, s[0:1], v0, v0, 1.0
	v_rcp_f32_e32 v2, v1
	v_div_scale_f32 v3, vcc, 1.0, v0, 1.0
	v_fma_f32 v4, -v1, v2, 1.0
	v_fmac_f32_e32 v2, v4, v2
	v_mul_f32_e32 v4, v3, v2
	v_fma_f32 v7, -v1, v4, v3
	v_fmac_f32_e32 v4, v7, v2
	v_fma_f32 v1, -v1, v4, v3
	v_add_f32_e32 v3, 1.0, v6
	v_rcp_f32_e32 v3, v3
	v_div_fmas_f32 v1, v1, v2, v4
	v_div_fixup_f32 v0, v1, v0, 1.0
	v_mul_f32_e32 v1, v3, v5
	v_mul_f32_e32 v1, v61, v1
	v_mul_f32_e32 v0, v0, v1
	v_cvt_pk_bf16_f32 v2, v0, v53
	v_lshl_add_u64 v[0:1], s[6:7], 0, v[8:9]
	global_store_short v[0:1], v2, off
